# attention: static prio for waves 4-7, cross-half row-max via v_permlane32_swap instead of ds_bpermute, epilogue 16x dwordx2 -> 8x dwordx4 via permlane32_swap
# speedup vs baseline: 1.0088x; 1.0088x over previous
; #define GAS __attribute__((address_space(1)))
; __device__ __forceinline__ unsigned pk2(float lo, float hi) { f32x2_t v = {lo, hi}; bf16x2_t b = __builtin_convertvector(v, bf16x2_t); return __builtin_bit_cast(unsigned, b); }
; __device__ __forceinline__ void attn_unit(const Ctx& C, int b, int h, int qb, const bf16* Q, const bf16* KN, const bf16* KR, const bf16* VT, bf16* OA) {
;     ...
;     const float ltot = lrow + __shfl_xor(lrow, 32), inv = 1.0f / ltot;
;     bf16* op = OA + (tok0 + qrow0 + r) * 2048 + h * 128 + 4 * hh;
; #pragma unroll
;     for (int d = 0; d < 4; ++d)
; #pragma unroll
;         for (int g = 0; g < 4; ++g)
;             *(GAS v2u*)(op + 32 * d + 8 * g) = (v2u){pk2(o[d][4 * g] * inv, o[d][4 * g + 1] * inv), pk2(o[d][4 * g + 2] * inv, o[d][4 * g + 3] * inv)};
.LBB0_491:
	ds_bpermute_b32 v0, v197, v206
	v_lshlrev_b64 v[66:67], 12, v[168:169]
	s_mov_b32 s29, s21
	v_lshl_add_u64 v[66:67], s[94:95], 0, v[66:67]
	v_lshl_add_u64 v[66:67], v[66:67], 0, s[28:29]
	s_waitcnt lgkmcnt(0)
	v_add_f32_e32 v0, v206, v0
	v_div_scale_f32 v68, s[0:1], v0, v0, 1.0
	v_rcp_f32_e32 v69, v68
	v_div_scale_f32 v70, vcc, 1.0, v0, 1.0
	s_add_i32 s49, s49, s76
	v_fma_f32 v71, -v68, v69, 1.0
	v_fmac_f32_e32 v69, v71, v69
	v_mul_f32_e32 v71, v70, v69
	v_fma_f32 v72, -v68, v71, v70
	v_fmac_f32_e32 v71, v72, v69
	v_fma_f32 v68, -v68, v71, v70
	v_div_fmas_f32 v68, v68, v69, v71
	v_div_fixup_f32 v68, v68, v0, 1.0
	v_lshlrev_b32_e32 v0, 1, v171
	v_lshl_add_u64 v[66:67], v[66:67], 0, v[0:1]
	v_mbcnt_lo_u32_b32 v70, -1, 0
	v_mbcnt_hi_u32_b32 v70, -1, v70
	v_and_b32_e32 v70, 32, v70
	v_lshrrev_b32_e32 v70, 2, v70
	v_add_co_u32_e32 v66, vcc, v66, v70
	s_nop 1
	v_addc_co_u32_e32 v67, vcc, 0, v67, vcc
	v_pk_mul_f32 v[2:3], v[2:3], v[68:69] op_sel_hi:[1,0]
	v_pk_mul_f32 v[4:5], v[4:5], v[68:69] op_sel_hi:[1,0]
	v_pk_mul_f32 v[6:7], v[6:7], v[68:69] op_sel_hi:[1,0]
	v_pk_mul_f32 v[8:9], v[8:9], v[68:69] op_sel_hi:[1,0]
	v_cvt_pk_bf16_f32 v2, v2, v3
	v_cvt_pk_bf16_f32 v3, v4, v5
	v_cvt_pk_bf16_f32 v4, v6, v7
	v_cvt_pk_bf16_f32 v5, v8, v9
	s_nop 1
	v_permlane32_swap_b32_e32 v2, v4
	v_permlane32_swap_b32_e32 v3, v5
	global_store_dwordx4 v[66:67], v[2:5], off offset:192
	v_pk_mul_f32 v[10:11], v[10:11], v[68:69] op_sel_hi:[1,0]
	v_pk_mul_f32 v[12:13], v[12:13], v[68:69] op_sel_hi:[1,0]
	v_pk_mul_f32 v[14:15], v[14:15], v[68:69] op_sel_hi:[1,0]
	v_pk_mul_f32 v[16:17], v[16:17], v[68:69] op_sel_hi:[1,0]
	v_cvt_pk_bf16_f32 v6, v10, v11
	v_cvt_pk_bf16_f32 v7, v12, v13
	v_cvt_pk_bf16_f32 v8, v14, v15
	v_cvt_pk_bf16_f32 v9, v16, v17
	s_nop 1
	v_permlane32_swap_b32_e32 v6, v8
	v_permlane32_swap_b32_e32 v7, v9
	global_store_dwordx4 v[66:67], v[6:9], off offset:224
	v_pk_mul_f32 v[18:19], v[18:19], v[68:69] op_sel_hi:[1,0]
	v_pk_mul_f32 v[20:21], v[20:21], v[68:69] op_sel_hi:[1,0]
	v_pk_mul_f32 v[22:23], v[22:23], v[68:69] op_sel_hi:[1,0]
	v_pk_mul_f32 v[24:25], v[24:25], v[68:69] op_sel_hi:[1,0]
	v_cvt_pk_bf16_f32 v18, v18, v19
	v_cvt_pk_bf16_f32 v19, v20, v21
	v_cvt_pk_bf16_f32 v20, v22, v23
	v_cvt_pk_bf16_f32 v21, v24, v25
	s_nop 1
	v_permlane32_swap_b32_e32 v18, v20
	v_permlane32_swap_b32_e32 v19, v21
	global_store_dwordx4 v[66:67], v[18:21], off offset:128
	v_pk_mul_f32 v[26:27], v[26:27], v[68:69] op_sel_hi:[1,0]
	v_pk_mul_f32 v[28:29], v[28:29], v[68:69] op_sel_hi:[1,0]
	v_pk_mul_f32 v[30:31], v[30:31], v[68:69] op_sel_hi:[1,0]
	v_pk_mul_f32 v[32:33], v[32:33], v[68:69] op_sel_hi:[1,0]
	v_cvt_pk_bf16_f32 v22, v26, v27
	v_cvt_pk_bf16_f32 v23, v28, v29
	v_cvt_pk_bf16_f32 v24, v30, v31
	v_cvt_pk_bf16_f32 v25, v32, v33
	s_nop 1
	v_permlane32_swap_b32_e32 v22, v24
	v_permlane32_swap_b32_e32 v23, v25
	global_store_dwordx4 v[66:67], v[22:25], off offset:160
	v_pk_mul_f32 v[34:35], v[34:35], v[68:69] op_sel_hi:[1,0]
	v_pk_mul_f32 v[36:37], v[36:37], v[68:69] op_sel_hi:[1,0]
	v_pk_mul_f32 v[38:39], v[38:39], v[68:69] op_sel_hi:[1,0]
	v_pk_mul_f32 v[40:41], v[40:41], v[68:69] op_sel_hi:[1,0]
	v_cvt_pk_bf16_f32 v34, v34, v35
	v_cvt_pk_bf16_f32 v35, v36, v37
	v_cvt_pk_bf16_f32 v36, v38, v39
	v_cvt_pk_bf16_f32 v37, v40, v41
	s_nop 1
	v_permlane32_swap_b32_e32 v34, v36
	v_permlane32_swap_b32_e32 v35, v37
	global_store_dwordx4 v[66:67], v[34:37], off offset:64
	v_pk_mul_f32 v[42:43], v[42:43], v[68:69] op_sel_hi:[1,0]
	v_pk_mul_f32 v[44:45], v[44:45], v[68:69] op_sel_hi:[1,0]
	v_pk_mul_f32 v[46:47], v[46:47], v[68:69] op_sel_hi:[1,0]
	v_pk_mul_f32 v[48:49], v[48:49], v[68:69] op_sel_hi:[1,0]
	v_cvt_pk_bf16_f32 v38, v42, v43
	v_cvt_pk_bf16_f32 v39, v44, v45
	v_cvt_pk_bf16_f32 v40, v46, v47
	v_cvt_pk_bf16_f32 v41, v48, v49
	s_nop 1
	v_permlane32_swap_b32_e32 v38, v40
	v_permlane32_swap_b32_e32 v39, v41
	global_store_dwordx4 v[66:67], v[38:41], off offset:96
	v_pk_mul_f32 v[50:51], v[50:51], v[68:69] op_sel_hi:[1,0]
	v_pk_mul_f32 v[52:53], v[52:53], v[68:69] op_sel_hi:[1,0]
	v_pk_mul_f32 v[54:55], v[54:55], v[68:69] op_sel_hi:[1,0]
	v_pk_mul_f32 v[56:57], v[56:57], v[68:69] op_sel_hi:[1,0]
	v_cvt_pk_bf16_f32 v50, v50, v51
	v_cvt_pk_bf16_f32 v51, v52, v53
	v_cvt_pk_bf16_f32 v52, v54, v55
	v_cvt_pk_bf16_f32 v53, v56, v57
	s_nop 1
	v_permlane32_swap_b32_e32 v50, v52
	v_permlane32_swap_b32_e32 v51, v53
	global_store_dwordx4 v[66:67], v[50:53], off
	v_pk_mul_f32 v[58:59], v[58:59], v[68:69] op_sel_hi:[1,0]
	v_pk_mul_f32 v[60:61], v[60:61], v[68:69] op_sel_hi:[1,0]
	v_pk_mul_f32 v[62:63], v[62:63], v[68:69] op_sel_hi:[1,0]
	v_pk_mul_f32 v[64:65], v[64:65], v[68:69] op_sel_hi:[1,0]
	v_cvt_pk_bf16_f32 v54, v58, v59
	v_cvt_pk_bf16_f32 v55, v60, v61
	v_cvt_pk_bf16_f32 v56, v62, v63
	v_cvt_pk_bf16_f32 v57, v64, v65
	s_nop 1
	v_permlane32_swap_b32_e32 v54, v56
	v_permlane32_swap_b32_e32 v55, v57
	global_store_dwordx4 v[66:67], v[54:57], off offset:32
	s_nop 1
	s_add_i32 s48, s48, s76
	s_cmpk_lt_i32 s49, 0x200
	s_cbranch_scc0 .LBB0_542

; __device__ __forceinline__ void attn_unit(const Ctx& C, int b, int h, int qb, const bf16* Q, const bf16* KN, const bf16* KR, const bf16* VT, bf16* OA) {
;     ...
;             float mx = s0[0];
; #pragma unroll
;             for (int i = 1; i < 16; ++i) mx = fmaxf(mx, s0[i]);
; #pragma unroll
;             for (int i = 0; i < 16; ++i) mx = fmaxf(mx, s1[i]);
;             mx = fmaxf(mx, __shfl_xor(mx, 32));
;             const bool need = mx > mrow + 8.0f;
;             if (__builtin_amdgcn_ballot_w64(need) != 0ull) {
;                 const float mnew = need ? mx : mrow, alpha = __builtin_amdgcn_exp2f(mrow - mnew);
.LBB0_514:
	s_nop 6
	v_max_f32_e32 v0, v67, v67
	v_max_f32_e32 v207, v66, v66
	v_max_f32_e32 v0, v207, v0
	v_max3_f32 v0, v0, v68, v69
	v_max3_f32 v0, v0, v70, v71
	v_max3_f32 v0, v0, v72, v73
	v_max3_f32 v0, v0, v74, v75
	v_max3_f32 v0, v0, v76, v77
	v_max3_f32 v0, v0, v78, v79
	v_max3_f32 v0, v0, v80, v81
	v_max3_f32 v0, v0, v82, v83
	v_max3_f32 v0, v0, v84, v85
	v_max3_f32 v0, v0, v86, v87
	v_max3_f32 v0, v0, v88, v89
	v_max3_f32 v0, v0, v90, v91
	v_max3_f32 v0, v0, v92, v93
	v_max3_f32 v0, v0, v94, v95
	v_max3_f32 v0, v0, v96, v97
	v_mov_b32_e32 v207, v0
	s_nop 1
	v_permlane32_swap_b32_e32 v207, v0
	v_max_f32_e32 v0, v0, v207
	v_add_f32_e32 v207, 0x41000000, v206
	v_cmp_gt_f32_e32 vcc, v0, v207
	s_cbranch_vccz .LBB0_516
	s_nop 0
	v_cndmask_b32_e32 v207, v206, v0, vcc
	v_sub_f32_e32 v0, v206, v207
	v_exp_f32_e32 v0, v0
	v_mov_b32_e32 v206, v207
	v_pk_mul_f32 v[64:65], v[64:65], v[0:1] op_sel_hi:[1,0]
	v_pk_mul_f32 v[62:63], v[62:63], v[0:1] op_sel_hi:[1,0]
	v_pk_mul_f32 v[60:61], v[60:61], v[0:1] op_sel_hi:[1,0]
	v_pk_mul_f32 v[58:59], v[58:59], v[0:1] op_sel_hi:[1,0]
	v_pk_mul_f32 v[56:57], v[56:57], v[0:1] op_sel_hi:[1,0]
	v_pk_mul_f32 v[54:55], v[54:55], v[0:1] op_sel_hi:[1,0]
	v_pk_mul_f32 v[52:53], v[52:53], v[0:1] op_sel_hi:[1,0]
	v_pk_mul_f32 v[50:51], v[50:51], v[0:1] op_sel_hi:[1,0]
	v_pk_mul_f32 v[48:49], v[48:49], v[0:1] op_sel_hi:[1,0]
	v_pk_mul_f32 v[46:47], v[46:47], v[0:1] op_sel_hi:[1,0]
	v_pk_mul_f32 v[44:45], v[44:45], v[0:1] op_sel_hi:[1,0]
	v_pk_mul_f32 v[42:43], v[42:43], v[0:1] op_sel_hi:[1,0]
	v_pk_mul_f32 v[40:41], v[40:41], v[0:1] op_sel_hi:[1,0]
	v_pk_mul_f32 v[38:39], v[38:39], v[0:1] op_sel_hi:[1,0]
	v_pk_mul_f32 v[36:37], v[36:37], v[0:1] op_sel_hi:[1,0]
	v_pk_mul_f32 v[34:35], v[34:35], v[0:1] op_sel_hi:[1,0]
	v_pk_mul_f32 v[32:33], v[32:33], v[0:1] op_sel_hi:[1,0]
	v_pk_mul_f32 v[30:31], v[30:31], v[0:1] op_sel_hi:[1,0]
	v_pk_mul_f32 v[28:29], v[28:29], v[0:1] op_sel_hi:[1,0]
	v_pk_mul_f32 v[26:27], v[26:27], v[0:1] op_sel_hi:[1,0]
	v_pk_mul_f32 v[24:25], v[24:25], v[0:1] op_sel_hi:[1,0]
	v_pk_mul_f32 v[22:23], v[22:23], v[0:1] op_sel_hi:[1,0]
	v_pk_mul_f32 v[20:21], v[20:21], v[0:1] op_sel_hi:[1,0]
	v_pk_mul_f32 v[18:19], v[18:19], v[0:1] op_sel_hi:[1,0]
	v_pk_mul_f32 v[16:17], v[16:17], v[0:1] op_sel_hi:[1,0]
	v_pk_mul_f32 v[14:15], v[14:15], v[0:1] op_sel_hi:[1,0]
	v_pk_mul_f32 v[12:13], v[12:13], v[0:1] op_sel_hi:[1,0]
	v_pk_mul_f32 v[10:11], v[10:11], v[0:1] op_sel_hi:[1,0]
	v_pk_mul_f32 v[8:9], v[8:9], v[0:1] op_sel_hi:[1,0]
	v_pk_mul_f32 v[6:7], v[6:7], v[0:1] op_sel_hi:[1,0]
	v_pk_mul_f32 v[4:5], v[4:5], v[0:1] op_sel_hi:[1,0]
	v_pk_mul_f32 v[2:3], v[2:3], v[0:1] op_sel_hi:[1,0]
	v_mul_f32_e32 v205, v205, v0

; #define GAS __attribute__((address_space(1)))
; __device__ __forceinline__ unsigned pk2(float lo, float hi) { f32x2_t v = {lo, hi}; bf16x2_t b = __builtin_convertvector(v, bf16x2_t); return __builtin_bit_cast(unsigned, b); }
; __device__ __forceinline__ void attn_unit(const Ctx& C, int b, int h, int qb, const bf16* Q, const bf16* KN, const bf16* KR, const bf16* VT, bf16* OA) {
;     ...
;     const int lane = tid & 63, r = lane & 31, hh = lane >> 5, w = __builtin_amdgcn_readfirstlane(tid >> 6);
;     const int qrow0 = qb * 256 + 32 * w;
;     const size_t tok0 = (size_t)b * SEQ;
;     bf16x8 qf[12];
;     { const bf16* qp = Q + (tok0 + qrow0 + r) * 3072 + h * 192 + 8 * hh;
; #pragma unroll
;       for (int s = 0; s < 12; ++s) qf[s] = *(const GAS bf16x8*)(qp + 16 * s); }
;     ...
;     const float ltot = lrow + __shfl_xor(lrow, 32), inv = 1.0f / ltot;
;     bf16* op = OA + (tok0 + qrow0 + r) * 2048 + h * 128 + 4 * hh;
; #pragma unroll
;     for (int d = 0; d < 4; ++d)
; #pragma unroll
;         for (int g = 0; g < 4; ++g)
;             *(GAS v2u*)(op + 32 * d + 8 * g) = (v2u){pk2(o[d][4 * g] * inv, o[d][4 * g + 1] * inv), pk2(o[d][4 * g + 2] * inv, o[d][4 * g + 3] * inv)};
.LBB0_517:
	v_and_b32_e32 v66, 64, v195
	v_xor_b32_e32 v0, 32, v195
	v_add_u32_e32 v66, 64, v66
	v_cmp_lt_i32_e32 vcc, v0, v66
	v_lshlrev_b64 v[66:67], 12, v[168:169]
	v_lshl_add_u64 v[66:67], s[94:95], 0, v[66:67]
	v_cndmask_b32_e32 v0, v195, v0, vcc
	v_lshlrev_b32_e32 v197, 2, v0
	ds_bpermute_b32 v0, v197, v205
	s_mov_b32 s29, s21
	v_lshl_add_u64 v[66:67], v[66:67], 0, s[28:29]
	s_waitcnt lgkmcnt(0)
	v_add_f32_e32 v0, v205, v0
	v_div_scale_f32 v68, s[4:5], v0, v0, 1.0
	v_rcp_f32_e32 v69, v68
	v_div_scale_f32 v70, vcc, 1.0, v0, 1.0
	s_lshl_b32 s5, s2, 8
	v_fma_f32 v71, -v68, v69, 1.0
	v_fmac_f32_e32 v69, v71, v69
	v_mul_f32_e32 v71, v70, v69
	v_fma_f32 v72, -v68, v71, v70
	v_fmac_f32_e32 v71, v72, v69
	v_fma_f32 v68, -v68, v71, v70
	v_div_fmas_f32 v68, v68, v69, v71
	v_div_fixup_f32 v68, v68, v0, 1.0
	v_lshlrev_b32_e32 v0, 1, v171
	v_lshl_add_u64 v[66:67], v[66:67], 0, v[0:1]
	v_mbcnt_lo_u32_b32 v70, -1, 0
	v_mbcnt_hi_u32_b32 v70, -1, v70
	v_and_b32_e32 v70, 32, v70
	v_lshrrev_b32_e32 v70, 2, v70
	v_add_co_u32_e32 v66, vcc, v66, v70
	s_nop 1
	v_addc_co_u32_e32 v67, vcc, 0, v67, vcc
	v_pk_mul_f32 v[2:3], v[2:3], v[68:69] op_sel_hi:[1,0]
	v_pk_mul_f32 v[4:5], v[4:5], v[68:69] op_sel_hi:[1,0]
	v_pk_mul_f32 v[6:7], v[6:7], v[68:69] op_sel_hi:[1,0]
	v_pk_mul_f32 v[8:9], v[8:9], v[68:69] op_sel_hi:[1,0]
	v_cvt_pk_bf16_f32 v2, v2, v3
	v_cvt_pk_bf16_f32 v3, v4, v5
	v_cvt_pk_bf16_f32 v4, v6, v7
	v_cvt_pk_bf16_f32 v5, v8, v9
	s_nop 1
	v_permlane32_swap_b32_e32 v2, v4
	v_permlane32_swap_b32_e32 v3, v5
	global_store_dwordx4 v[66:67], v[2:5], off offset:192
	v_pk_mul_f32 v[10:11], v[10:11], v[68:69] op_sel_hi:[1,0]
	v_pk_mul_f32 v[12:13], v[12:13], v[68:69] op_sel_hi:[1,0]
	v_pk_mul_f32 v[14:15], v[14:15], v[68:69] op_sel_hi:[1,0]
	v_pk_mul_f32 v[16:17], v[16:17], v[68:69] op_sel_hi:[1,0]
	v_cvt_pk_bf16_f32 v6, v10, v11
	v_cvt_pk_bf16_f32 v7, v12, v13
	v_cvt_pk_bf16_f32 v8, v14, v15
	v_cvt_pk_bf16_f32 v9, v16, v17
	s_nop 1
	v_permlane32_swap_b32_e32 v6, v8
	v_permlane32_swap_b32_e32 v7, v9
	global_store_dwordx4 v[66:67], v[6:9], off offset:224
	v_pk_mul_f32 v[18:19], v[18:19], v[68:69] op_sel_hi:[1,0]
	v_pk_mul_f32 v[20:21], v[20:21], v[68:69] op_sel_hi:[1,0]
	v_pk_mul_f32 v[22:23], v[22:23], v[68:69] op_sel_hi:[1,0]
	v_pk_mul_f32 v[24:25], v[24:25], v[68:69] op_sel_hi:[1,0]
	v_cvt_pk_bf16_f32 v18, v18, v19
	v_cvt_pk_bf16_f32 v19, v20, v21
	v_cvt_pk_bf16_f32 v20, v22, v23
	v_cvt_pk_bf16_f32 v21, v24, v25
	s_nop 1
	v_permlane32_swap_b32_e32 v18, v20
	v_permlane32_swap_b32_e32 v19, v21
	global_store_dwordx4 v[66:67], v[18:21], off offset:128
	v_pk_mul_f32 v[26:27], v[26:27], v[68:69] op_sel_hi:[1,0]
	v_pk_mul_f32 v[28:29], v[28:29], v[68:69] op_sel_hi:[1,0]
	v_pk_mul_f32 v[30:31], v[30:31], v[68:69] op_sel_hi:[1,0]
	v_pk_mul_f32 v[32:33], v[32:33], v[68:69] op_sel_hi:[1,0]
	v_cvt_pk_bf16_f32 v22, v26, v27
	v_cvt_pk_bf16_f32 v23, v28, v29
	v_cvt_pk_bf16_f32 v24, v30, v31
	v_cvt_pk_bf16_f32 v25, v32, v33
	s_nop 1
	v_permlane32_swap_b32_e32 v22, v24
	v_permlane32_swap_b32_e32 v23, v25
	global_store_dwordx4 v[66:67], v[22:25], off offset:160
	v_pk_mul_f32 v[34:35], v[34:35], v[68:69] op_sel_hi:[1,0]
	v_pk_mul_f32 v[36:37], v[36:37], v[68:69] op_sel_hi:[1,0]
	v_pk_mul_f32 v[38:39], v[38:39], v[68:69] op_sel_hi:[1,0]
	v_pk_mul_f32 v[40:41], v[40:41], v[68:69] op_sel_hi:[1,0]
	v_cvt_pk_bf16_f32 v34, v34, v35
	v_cvt_pk_bf16_f32 v35, v36, v37
	v_cvt_pk_bf16_f32 v36, v38, v39
	v_cvt_pk_bf16_f32 v37, v40, v41
	s_nop 1
	v_permlane32_swap_b32_e32 v34, v36
	v_permlane32_swap_b32_e32 v35, v37
	global_store_dwordx4 v[66:67], v[34:37], off offset:64
	v_pk_mul_f32 v[42:43], v[42:43], v[68:69] op_sel_hi:[1,0]
	v_pk_mul_f32 v[44:45], v[44:45], v[68:69] op_sel_hi:[1,0]
	v_pk_mul_f32 v[46:47], v[46:47], v[68:69] op_sel_hi:[1,0]
	v_pk_mul_f32 v[48:49], v[48:49], v[68:69] op_sel_hi:[1,0]
	v_cvt_pk_bf16_f32 v38, v42, v43
	v_cvt_pk_bf16_f32 v39, v44, v45
	v_cvt_pk_bf16_f32 v40, v46, v47
	v_cvt_pk_bf16_f32 v41, v48, v49
	s_nop 1
	v_permlane32_swap_b32_e32 v38, v40
	v_permlane32_swap_b32_e32 v39, v41
	global_store_dwordx4 v[66:67], v[38:41], off offset:96
	v_pk_mul_f32 v[50:51], v[50:51], v[68:69] op_sel_hi:[1,0]
	v_pk_mul_f32 v[52:53], v[52:53], v[68:69] op_sel_hi:[1,0]
	v_pk_mul_f32 v[54:55], v[54:55], v[68:69] op_sel_hi:[1,0]
	v_pk_mul_f32 v[56:57], v[56:57], v[68:69] op_sel_hi:[1,0]
	v_cvt_pk_bf16_f32 v50, v50, v51
	v_cvt_pk_bf16_f32 v51, v52, v53
	v_cvt_pk_bf16_f32 v52, v54, v55
	v_cvt_pk_bf16_f32 v53, v56, v57
	s_nop 1
	v_permlane32_swap_b32_e32 v50, v52
	v_permlane32_swap_b32_e32 v51, v53
	global_store_dwordx4 v[66:67], v[50:53], off
	v_pk_mul_f32 v[58:59], v[58:59], v[68:69] op_sel_hi:[1,0]
	v_pk_mul_f32 v[60:61], v[60:61], v[68:69] op_sel_hi:[1,0]
	v_pk_mul_f32 v[62:63], v[62:63], v[68:69] op_sel_hi:[1,0]
	v_pk_mul_f32 v[64:65], v[64:65], v[68:69] op_sel_hi:[1,0]
	v_cvt_pk_bf16_f32 v54, v58, v59
	v_cvt_pk_bf16_f32 v55, v60, v61
	v_cvt_pk_bf16_f32 v56, v62, v63
	v_cvt_pk_bf16_f32 v57, v64, v65
	s_nop 1
	v_permlane32_swap_b32_e32 v54, v56
	v_permlane32_swap_b32_e32 v55, v57
	global_store_dwordx4 v[66:67], v[54:57], off offset:32
	s_nop 1
	v_mov_b32_e32 v22, v192
	v_mov_b64_e32 v[2:3], s[66:67]
	v_readfirstlane_b32 s4, v22
	s_ashr_i32 s4, s4, 1
	s_and_b32 s29, s4, 0xffffffe0
	s_add_i32 s29, s29, s5
	s_ashr_i32 s4, s29, 31
	v_and_b32_e32 v4, 31, v22
	s_add_u32 s5, s0, s29
	v_or_b32_e32 v168, s5, v4
	s_addc_u32 s6, s1, s4
	v_mad_u64_u32 v[2:3], s[4:5], v168, s44, v[2:3]
	v_bfe_u32 v23, v22, 5, 1
	v_mad_i32_i24 v3, s6, v194, v3
	v_lshl_add_u64 v[2:3], v[2:3], 0, s[20:21]
	v_lshlrev_b32_e32 v170, 4, v23
	v_mov_b32_e32 v171, v1
	v_lshl_add_u64 v[2:3], v[2:3], 0, v[170:171]
; #define GAS __attribute__((address_space(1)))
; #define ATT_STORE(buf) do { LAS unsigned char* kb_ = C.lds + (buf) * BUF_B; _Pragma("unroll") for (int i = 0; i < 3; ++i) *(LAS v4u*)(kb_ + kkey[i] * (KP * 2) + kpart[i] * 16) = kreg[i]; \
;         _Pragma("unroll") for (int i = 0; i < 2; ++i) *(LAS v4u*)(kb_ + KT_B + vdst[i]) = vreg[i]; } while (0)
; __device__ __forceinline__ void attn_unit(const Ctx& C, int b, int h, int qb, const bf16* Q, const bf16* KN, const bf16* KR, const bf16* VT, bf16* OA) {
;     ...
;     const int lane = tid & 63, r = lane & 31, hh = lane >> 5, w = __builtin_amdgcn_readfirstlane(tid >> 6);
;     const int qrow0 = qb * 256 + 32 * w;
;     const size_t tok0 = (size_t)b * SEQ;
;     bf16x8 qf[12];
;     { const bf16* qp = Q + (tok0 + qrow0 + r) * 3072 + h * 192 + 8 * hh;
; #pragma unroll
;       for (int s = 0; s < 12; ++s) qf[s] = *(const GAS bf16x8*)(qp + 16 * s); }
;     f32x16 o[4];
; #pragma unroll
;     for (int d = 0; d < 4; ++d)
; #pragma unroll
;         for (int i = 0; i < 16; ++i) o[d][i] = 0.f;
;     float mrow = -1e30f, lrow = 0.f;
;     const int nkt = (qb + 1) * 4;
;     int kkey[3], kpart[3];
; #pragma unroll
;     for (int i = 0; i < 3; ++i) { const int p = tid + 512 * i; kkey[i] = p / 24; kpart[i] = p % 24; }
;     const bf16* vsrc[2]; int vdst[2];
; #pragma unroll
;     for (int i = 0; i < 2; ++i) { const int p = tid + 512 * i, key = p >> 4, part = p & 15; vsrc[i] = VT + (tok0 + key) * 2048 + h * 128 + part * 8; vdst[i] = key * VP * 2 + part * 16; }
;     const int vtr0 = (4 * hh + ((lane & 15) >> 2)) * (VP * 2) + (16 * ((lane >> 4) & 1) + 4 * (lane & 3)) * 2;
;     v4u kreg[3], vreg[2];
;     ...
;     ATT_LOAD(0); ATT_STORE(0);
	global_load_dwordx4 v[98:101], v[2:3], off
	global_load_dwordx4 v[102:105], v[2:3], off offset:32
	global_load_dwordx4 v[106:109], v[2:3], off offset:64
	global_load_dwordx4 v[110:113], v[2:3], off offset:96
	global_load_dwordx4 v[114:117], v[2:3], off offset:128
	global_load_dwordx4 v[118:121], v[2:3], off offset:160
	global_load_dwordx4 v[122:125], v[2:3], off offset:192
	global_load_dwordx4 v[126:129], v[2:3], off offset:224
	global_load_dwordx4 v[130:133], v[2:3], off offset:256
	global_load_dwordx4 v[134:137], v[2:3], off offset:288
	global_load_dwordx4 v[138:141], v[2:3], off offset:320
	global_load_dwordx4 v[142:145], v[2:3], off offset:352
	v_mul_hi_i32 v0, v22, s45
	v_lshrrev_b32_e32 v2, 31, v0
	v_ashrrev_i32_e32 v0, 2, v0
	v_add_u32_e32 v6, v0, v2
	v_mul_lo_u32 v0, v6, 24
	v_sub_u32_e32 v24, v22, v0
	v_ashrrev_i32_e32 v7, 31, v6
	v_mov_b32_e32 v169, s6
	v_lshl_add_u64 v[10:11], s[0:1], 0, v[6:7]
	v_cmp_gt_i32_e64 s[4:5], 16, v24
	v_cmp_lt_i32_e32 vcc, 15, v24
	v_lshlrev_b32_e32 v2, 3, v24
	s_and_saveexec_b64 s[6:7], vcc
	s_xor_b64 s[6:7], exec, s[6:7]
	v_lshlrev_b64 v[8:9], 7, v[10:11]
	v_lshl_add_u64 v[8:9], s[16:17], 0, v[8:9]
	v_mov_b32_e32 v3, v1
	v_lshl_add_u64 v[8:9], v[2:3], 1, v[8:9]
	v_lshl_add_u64 v[8:9], v[8:9], 0, s[22:23]
	s_or_saveexec_b64 s[6:7], s[6:7]
	v_ashrrev_i32_e32 v5, 31, v2
	s_xor_b64 exec, exec, s[6:7]
	v_lshlrev_b64 v[8:9], 12, v[10:11]
	v_lshl_add_u64 v[8:9], s[30:31], 0, v[8:9]
	v_mov_b32_e32 v3, v5
	v_lshl_add_u64 v[8:9], v[2:3], 1, v[8:9]
	s_or_b64 exec, exec, s[6:7]
	global_load_dwordx4 v[146:149], v[8:9], off
	v_add_u32_e32 v10, 0x200, v22
	v_mul_hi_i32 v0, v10, s45
	v_lshrrev_b32_e32 v3, 31, v0
	v_ashrrev_i32_e32 v0, 2, v0
	v_add_u32_e32 v12, v0, v3
	v_mul_lo_u32 v0, v12, 24
	v_sub_u32_e32 v3, v10, v0
	v_ashrrev_i32_e32 v13, 31, v12
	v_lshl_add_u64 v[16:17], s[0:1], 0, v[12:13]
	v_cmp_gt_i32_e64 s[6:7], 16, v3
	v_cmp_lt_i32_e32 vcc, 15, v3
	v_lshlrev_b32_e32 v8, 3, v3
	s_and_saveexec_b64 s[8:9], vcc
	s_xor_b64 s[8:9], exec, s[8:9]
	v_lshlrev_b64 v[14:15], 7, v[16:17]
	v_lshl_add_u64 v[14:15], s[16:17], 0, v[14:15]
	v_mov_b32_e32 v9, v1
	v_lshl_add_u64 v[14:15], v[8:9], 1, v[14:15]
	v_lshl_add_u64 v[14:15], v[14:15], 0, s[22:23]
	s_or_saveexec_b64 s[8:9], s[8:9]
	v_ashrrev_i32_e32 v11, 31, v8
	s_xor_b64 exec, exec, s[8:9]
	v_lshlrev_b64 v[14:15], 12, v[16:17]
	v_lshl_add_u64 v[14:15], s[30:31], 0, v[14:15]
	v_mov_b32_e32 v9, v11
	v_lshl_add_u64 v[14:15], v[8:9], 1, v[14:15]
	s_or_b64 exec, exec, s[8:9]
	global_load_dwordx4 v[150:153], v[14:15], off
	v_add_u32_e32 v0, 0x400, v22
	v_mul_hi_i32 v9, v0, s45
	v_lshrrev_b32_e32 v14, 31, v9
	v_ashrrev_i32_e32 v9, 2, v9
	v_add_u32_e32 v16, v9, v14
	v_mul_lo_u32 v9, v16, 24
	v_sub_u32_e32 v9, v0, v9
	v_ashrrev_i32_e32 v17, 31, v16
	v_lshl_add_u64 v[20:21], s[0:1], 0, v[16:17]
	v_cmp_gt_i32_e64 s[8:9], 16, v9
	v_cmp_lt_i32_e32 vcc, 15, v9
	v_lshlrev_b32_e32 v0, 3, v9
	s_and_saveexec_b64 s[42:43], vcc
	s_xor_b64 s[42:43], exec, s[42:43]
	v_lshlrev_b64 v[14:15], 7, v[20:21]
	v_lshl_add_u64 v[14:15], s[16:17], 0, v[14:15]
	v_lshl_add_u64 v[14:15], v[0:1], 1, v[14:15]
	v_lshl_add_u64 v[18:19], v[14:15], 0, s[22:23]
	s_or_saveexec_b64 s[42:43], s[42:43]
	v_mov_b64_e32 v[14:15], v[0:1]
	s_xor_b64 exec, exec, s[42:43]
	v_lshlrev_b64 v[14:15], 12, v[20:21]
	v_lshl_add_u64 v[18:19], s[30:31], 0, v[14:15]
	v_ashrrev_i32_e32 v15, 31, v0
	v_mov_b32_e32 v14, v0
	v_lshl_add_u64 v[18:19], v[14:15], 1, v[18:19]
	s_or_b64 exec, exec, s[42:43]
	v_ashrrev_i32_e32 v28, 4, v22
	v_ashrrev_i32_e32 v32, 4, v10
	v_lshlrev_b32_e32 v20, 4, v22
	v_ashrrev_i32_e32 v29, 31, v28
	v_ashrrev_i32_e32 v33, 31, v32
	v_and_b32_e32 v20, 0xf0, v20
	v_mov_b32_e32 v21, v1
	v_lshl_add_u64 v[30:31], s[0:1], 0, v[28:29]
	v_lshl_add_u64 v[34:35], s[0:1], 0, v[32:33]
	v_lshl_add_u64 v[26:27], s[36:37], 0, v[20:21]
	v_lshlrev_b64 v[30:31], 12, v[30:31]
	v_lshlrev_b64 v[34:35], 12, v[34:35]
	v_lshl_add_u64 v[30:31], v[26:27], 0, v[30:31]
	v_lshl_add_u64 v[26:27], v[26:27], 0, v[34:35]
	global_load_dwordx4 v[154:157], v[18:19], off
	global_load_dwordx4 v[158:161], v[30:31], off
	global_load_dwordx4 v[162:165], v[26:27], off
	s_and_b32 s0, s48, 3
	s_lshl_b32 s20, s2, 2
	s_lshl_b32 s30, s0, 8
	v_lshlrev_b32_e32 v171, 2, v23
	v_lshrrev_b32_e32 v26, 2, v22
	v_and_b32_e32 v27, 16, v22
	v_lshlrev_b32_e32 v30, 2, v22
	s_or_b32 s2, s29, 31
	s_add_i32 s20, s20, 4
	v_mad_u64_u32 v[172:173], s[0:1], v28, s46, v[20:21]
	v_mad_u64_u32 v[174:175], s[0:1], v32, s46, v[20:21]
	s_addk_i32 s30, 0x100
	v_mul_lo_u32 v200, v12, s47
	v_lshlrev_b64 v[22:23], 12, v[12:13]
	v_lshlrev_b64 v[12:13], 7, v[12:13]
	v_and_or_b32 v26, v26, 3, v171
	v_and_or_b32 v27, v30, 12, v27
	s_add_u32 s0, s3, s40
	v_lshlrev_b32_e32 v203, 4, v9
	v_mov_b32_e32 v9, v1
	v_lshl_add_u64 v[12:13], s[34:35], 0, v[12:13]
	v_mul_u32_u24_e32 v173, 0x140, v26
	v_lshlrev_b32_e32 v175, 1, v27
	v_lshlrev_b64 v[26:27], 12, v[28:29]
	v_lshlrev_b64 v[28:29], 12, v[32:33]
	s_addc_u32 s1, 0, s41
	v_mul_lo_u32 v202, v16, s47
	v_mov_b32_e32 v10, v8
	v_lshlrev_b64 v[18:19], 12, v[16:17]
	v_lshlrev_b64 v[16:17], 7, v[16:17]
	v_lshl_add_u64 v[178:179], v[8:9], 1, v[12:13]
	v_lshl_add_u64 v[8:9], s[0:1], 0, v[26:27]
	v_lshl_add_u64 v[12:13], s[0:1], 0, v[28:29]
	s_add_u32 s0, s3, s38
	v_mul_lo_u32 v198, v6, s47
	v_lshlrev_b32_e32 v199, 4, v24
	v_lshlrev_b64 v[24:25], 12, v[6:7]
	v_lshl_add_u64 v[16:17], s[34:35], 0, v[16:17]
	s_addc_u32 s1, 0, s39
	v_lshlrev_b32_e32 v201, 4, v3
	v_mul_u32_u24_e32 v204, 0x190, v4
	v_or_b32_e32 v205, s29, v4
	v_mov_b32_e32 v4, v2
	v_lshlrev_b64 v[6:7], 7, v[6:7]
	v_add3_u32 v30, 0, v198, v199
	v_lshl_add_u64 v[176:177], v[0:1], 1, v[16:17]
	v_lshl_add_u64 v[180:181], v[8:9], 0, v[20:21]
	v_lshl_add_u64 v[8:9], s[0:1], 0, v[18:19]
	v_lshl_add_u64 v[16:17], s[0:1], 0, v[24:25]
	v_mov_b32_e32 v3, v1
	v_add3_u32 v31, 0, v200, v201
	v_add3_u32 v34, 0, v202, v203
	s_waitcnt vmcnt(4)
; #define ATT_STORE(buf) do { LAS unsigned char* kb_ = C.lds + (buf) * BUF_B; _Pragma("unroll") for (int i = 0; i < 3; ++i) *(LAS v4u*)(kb_ + kkey[i] * (KP * 2) + kpart[i] * 16) = kreg[i]; \
;         _Pragma("unroll") for (int i = 0; i < 2; ++i) *(LAS v4u*)(kb_ + KT_B + vdst[i]) = vreg[i]; } while (0)
; __device__ __forceinline__ void attn_unit(const Ctx& C, int b, int h, int qb, const bf16* Q, const bf16* KN, const bf16* KR, const bf16* VT, bf16* OA) {
;     ...
;     f32x16 o[4];
; #pragma unroll
;     for (int d = 0; d < 4; ++d)
; #pragma unroll
;         for (int i = 0; i < 16; ++i) o[d][i] = 0.f;
;     float mrow = -1e30f, lrow = 0.f;
;     const int nkt = (qb + 1) * 4;
;     int kkey[3], kpart[3];
; #pragma unroll
;     for (int i = 0; i < 3; ++i) { const int p = tid + 512 * i; kkey[i] = p / 24; kpart[i] = p % 24; }
;     const bf16* vsrc[2]; int vdst[2];
; #pragma unroll
;     for (int i = 0; i < 2; ++i) { const int p = tid + 512 * i, key = p >> 4, part = p & 15; vsrc[i] = VT + (tok0 + key) * 2048 + h * 128 + part * 8; vdst[i] = key * VP * 2 + part * 16; }
;     const int vtr0 = (4 * hh + ((lane & 15) >> 2)) * (VP * 2) + (16 * ((lane >> 4) & 1) + 4 * (lane & 3)) * 2;
;     v4u kreg[3], vreg[2];
;     ...
;     ATT_LOAD(0); ATT_STORE(0);
;     __syncthreads();
	ds_write_b128 v30, v[146:149]
	s_waitcnt vmcnt(3)
	ds_write_b128 v31, v[150:153]
	v_add_u32_e32 v0, 0, v172
	v_add_u32_e32 v30, 0, v174
	v_lshl_add_u64 v[182:183], v[12:13], 0, v[20:21]
	v_lshl_add_u64 v[12:13], s[0:1], 0, v[22:23]
	v_lshl_add_u64 v[184:185], v[14:15], 1, v[8:9]
	v_lshl_add_u64 v[188:189], v[4:5], 1, v[16:17]
	v_lshl_add_u64 v[4:5], s[34:35], 0, v[6:7]
	v_mov_b32_e32 v14, v1
	v_mov_b32_e32 v15, v1
	v_lshl_add_u64 v[186:187], v[10:11], 1, v[12:13]
	v_lshl_add_u64 v[190:191], v[2:3], 1, v[4:5]
	v_mov_b32_e32 v2, v1
	v_mov_b32_e32 v4, v1
	v_mov_b32_e32 v5, v1
	s_waitcnt vmcnt(2)
	ds_write_b128 v34, v[154:157]
	s_waitcnt vmcnt(1)
	ds_write_b128 v0, v[158:161] offset:25600
	s_waitcnt vmcnt(0)
	ds_write_b128 v30, v[162:165] offset:25600
	v_mov_b32_e32 v0, v1
	v_mov_b32_e32 v6, v1
	v_mov_b32_e32 v7, v1
	v_mov_b32_e32 v8, v1
	v_mov_b32_e32 v9, v1
	v_mov_b32_e32 v10, v1
	v_mov_b32_e32 v11, v1
	v_mov_b32_e32 v12, v1
	v_mov_b32_e32 v13, v1
	v_mov_b64_e32 v[64:65], v[14:15]
	v_mov_b64_e32 v[48:49], v[14:15]
	v_mov_b64_e32 v[32:33], v[14:15]
	v_mov_b64_e32 v[62:63], v[12:13]
	v_mov_b64_e32 v[60:61], v[10:11]
	v_mov_b64_e32 v[58:59], v[8:9]
	v_mov_b64_e32 v[56:57], v[6:7]
	v_mov_b64_e32 v[54:55], v[4:5]
	v_mov_b64_e32 v[52:53], v[2:3]
	v_mov_b64_e32 v[50:51], v[0:1]
	v_mov_b64_e32 v[46:47], v[12:13]
	v_mov_b64_e32 v[44:45], v[10:11]
	v_mov_b64_e32 v[42:43], v[8:9]
	v_mov_b64_e32 v[40:41], v[6:7]
	v_mov_b64_e32 v[38:39], v[4:5]
	v_mov_b64_e32 v[36:37], v[2:3]
	v_mov_b64_e32 v[34:35], v[0:1]
	v_mov_b64_e32 v[30:31], v[12:13]
	v_mov_b64_e32 v[28:29], v[10:11]
	v_mov_b64_e32 v[26:27], v[8:9]
	v_mov_b64_e32 v[24:25], v[6:7]
	v_mov_b64_e32 v[22:23], v[4:5]
	v_mov_b64_e32 v[20:21], v[2:3]
	v_mov_b64_e32 v[18:19], v[0:1]
	v_mov_b64_e32 v[16:17], v[14:15]
	s_mov_b32 s3, 0
	v_mov_b32_e32 v207, 0xf149f2ca
	v_mov_b32_e32 v206, 0
	v_mov_b64_e32 v[14:15], v[12:13]
	v_mov_b64_e32 v[12:13], v[10:11]
	v_mov_b64_e32 v[10:11], v[8:9]
	v_mov_b64_e32 v[8:9], v[6:7]
	v_mov_b64_e32 v[6:7], v[4:5]
	v_mov_b64_e32 v[4:5], v[2:3]
	v_mov_b64_e32 v[2:3], v[0:1]
	s_mov_b32 s33, 0
	s_waitcnt lgkmcnt(0)
	s_barrier

; __device__ __forceinline__ void attn_unit(const Ctx& C, int b, int h, int qb, const bf16* Q, const bf16* KN, const bf16* KR, const bf16* VT, bf16* OA) {
;     ...
;             float mx = s0[0];
; #pragma unroll
;             for (int i = 1; i < 16; ++i) mx = fmaxf(mx, s0[i]);
; #pragma unroll
;             for (int i = 0; i < 16; ++i) mx = fmaxf(mx, s1[i]);
;             mx = fmaxf(mx, __shfl_xor(mx, 32));
;             const bool need = mx > mrow + 8.0f;
;             if (__builtin_amdgcn_ballot_w64(need) != 0ull) {
;                 const float mnew = need ? mx : mrow, alpha = __builtin_amdgcn_exp2f(mrow - mnew);
;                 lrow *= alpha; mrow = mnew;
; #pragma unroll
;                 for (int d = 0; d < 4; ++d)
; #pragma unroll
;                     for (int i = 0; i < 16; ++i) o[d][i] *= alpha;
;             }
.LBB0_539:
	s_nop 6
	v_max_f32_e32 v0, v67, v67
	v_max_f32_e32 v208, v66, v66
	v_max_f32_e32 v0, v208, v0
	v_max3_f32 v0, v0, v68, v69
	v_max3_f32 v0, v0, v70, v71
	v_max3_f32 v0, v0, v72, v73
	v_max3_f32 v0, v0, v74, v75
	v_max3_f32 v0, v0, v76, v77
	v_max3_f32 v0, v0, v78, v79
	v_max3_f32 v0, v0, v80, v81
	v_max3_f32 v0, v0, v82, v83
	v_max3_f32 v0, v0, v84, v85
	v_max3_f32 v0, v0, v86, v87
	v_max3_f32 v0, v0, v88, v89
	v_max3_f32 v0, v0, v90, v91
	v_max3_f32 v0, v0, v92, v93
	v_max3_f32 v0, v0, v94, v95
	v_max3_f32 v0, v0, v96, v97
	v_mov_b32_e32 v208, v0
	s_nop 1
	v_permlane32_swap_b32_e32 v208, v0
	v_max_f32_e32 v0, v0, v208
	v_add_f32_e32 v208, 0x41000000, v207
	v_cmp_gt_f32_e32 vcc, v0, v208
	s_cbranch_vccz .LBB0_541
	s_nop 0
	v_cndmask_b32_e32 v208, v207, v0, vcc
	v_sub_f32_e32 v0, v207, v208
	v_exp_f32_e32 v0, v0
	v_mov_b32_e32 v207, v208
	v_pk_mul_f32 v[64:65], v[64:65], v[0:1] op_sel_hi:[1,0]
	v_pk_mul_f32 v[62:63], v[62:63], v[0:1] op_sel_hi:[1,0]
	v_pk_mul_f32 v[60:61], v[60:61], v[0:1] op_sel_hi:[1,0]
	v_pk_mul_f32 v[58:59], v[58:59], v[0:1] op_sel_hi:[1,0]
	v_pk_mul_f32 v[56:57], v[56:57], v[0:1] op_sel_hi:[1,0]
	v_pk_mul_f32 v[54:55], v[54:55], v[0:1] op_sel_hi:[1,0]
	v_pk_mul_f32 v[52:53], v[52:53], v[0:1] op_sel_hi:[1,0]
	v_pk_mul_f32 v[50:51], v[50:51], v[0:1] op_sel_hi:[1,0]
	v_pk_mul_f32 v[48:49], v[48:49], v[0:1] op_sel_hi:[1,0]
	v_pk_mul_f32 v[46:47], v[46:47], v[0:1] op_sel_hi:[1,0]
	v_pk_mul_f32 v[44:45], v[44:45], v[0:1] op_sel_hi:[1,0]
	v_pk_mul_f32 v[42:43], v[42:43], v[0:1] op_sel_hi:[1,0]
	v_pk_mul_f32 v[40:41], v[40:41], v[0:1] op_sel_hi:[1,0]
	v_pk_mul_f32 v[38:39], v[38:39], v[0:1] op_sel_hi:[1,0]
	v_pk_mul_f32 v[36:37], v[36:37], v[0:1] op_sel_hi:[1,0]
	v_pk_mul_f32 v[34:35], v[34:35], v[0:1] op_sel_hi:[1,0]
	v_pk_mul_f32 v[32:33], v[32:33], v[0:1] op_sel_hi:[1,0]
	v_pk_mul_f32 v[30:31], v[30:31], v[0:1] op_sel_hi:[1,0]
	v_pk_mul_f32 v[28:29], v[28:29], v[0:1] op_sel_hi:[1,0]
	v_pk_mul_f32 v[26:27], v[26:27], v[0:1] op_sel_hi:[1,0]
	v_pk_mul_f32 v[24:25], v[24:25], v[0:1] op_sel_hi:[1,0]
	v_pk_mul_f32 v[22:23], v[22:23], v[0:1] op_sel_hi:[1,0]
	v_pk_mul_f32 v[20:21], v[20:21], v[0:1] op_sel_hi:[1,0]
	v_pk_mul_f32 v[18:19], v[18:19], v[0:1] op_sel_hi:[1,0]
	v_pk_mul_f32 v[16:17], v[16:17], v[0:1] op_sel_hi:[1,0]
	v_pk_mul_f32 v[14:15], v[14:15], v[0:1] op_sel_hi:[1,0]
	v_pk_mul_f32 v[12:13], v[12:13], v[0:1] op_sel_hi:[1,0]
	v_pk_mul_f32 v[10:11], v[10:11], v[0:1] op_sel_hi:[1,0]
	v_pk_mul_f32 v[8:9], v[8:9], v[0:1] op_sel_hi:[1,0]
	v_pk_mul_f32 v[6:7], v[6:7], v[0:1] op_sel_hi:[1,0]
	v_pk_mul_f32 v[4:5], v[4:5], v[0:1] op_sel_hi:[1,0]
	v_pk_mul_f32 v[2:3], v[2:3], v[0:1] op_sel_hi:[1,0]
	v_mul_f32_e32 v206, v206, v0
